# v79 + attention round-1 unit mapping keeps each head on the same XCD (p = ((255-bx)&~7)|(bx&7))
# baseline (speedup 1.0000x reference)
; template<int THRL> __device__ __forceinline__ void attn_unit(int qb,const bf16*Q,const bf16*__restrict__ K,const bf16*__restrict__ V,bf16*O,char*shm){
;   int tid=threadIdx.x; asm volatile("":"+v"(tid)); const int lane=tid&63,r32=lane&31,hi=lane>>5; const int wid=__builtin_amdgcn_readfirstlane(tid>>6);
;   const int q0=qb*QB;
;   const bf16*Qw=Q+(long)(q0+wid*QBLK)*PZ;
;   const bf16*Kh=K,*Vh=V;
;   const unsigned lds0=(unsigned)(uintptr_t)shm;
;   float*wsf=(float*)(shm+LDS_WS)+wid*64;
;   const bf16*ksrc=Kh+(long)lane*PZ+wid*8;
;   const bf16*vsrc=Vh+(long)(16*(wid&3)+(lane>>2))*PZ+(wid>>2)*32+(lane&3)*8;
;   const unsigned kdst=lds0+LDS_K+wid*1024, vdst=lds0+LDS_V+wid*1024;
;     ...
;   const int vb0=(int)(lds0+LDS_V)+((lane>>4)&1)*32+(lane&3)*8+(4*hi+((lane&15)>>2))*64;
;   const char*Kbase=shm+LDS_K; bf16x8 kf[8];
;   const lds_cptr shm3=(lds_cptr)shm; const lds_cptr kp0=shm3+LDS_K+hi*1024+r32*16; const lds_cptr vp0=shm3+LDS_V+((lane>>4)&1)*32+(lane&3)*8+(4*hi+((lane&15)>>2))*64;
;   const int NT=(q0+QB)/KVBLK;
;   DMA_K(0,0);DMA_V(0,0);DMA_K(1,SLOTB);
;   bf16x8 qr[4];
;   #pragma unroll
;   for(int d0=0;d0<4;++d0)qr[d0]=*reinterpret_cast<const bf16x8*>(&Qw[(long)r32*PZ+d0*16+hi*8]);
;   float mhat=0.f,l_reg=0.f;f32x16 o[4];o[0]=f32x16{};o[1]=f32x16{};o[2]=f32x16{};o[3]=f32x16{};f32x16 negm=f32x16{};asm volatile("":"+v"(negm));
;   const int qrel=wid*QBLK+r32;
;     ...
;   bool resc=false;
;     ...
;   f32x16 pA0,pA1,pB0,pB1;
;   int sl_prev=0,sl_cur=0,sl_next=SLOTB;
;     ...
;   DMA_K(2,2*SLOTB);
;   WAIT_BAR(4);
; __global__ void __launch_bounds__(NTHR, 2) trunk_fwd(Args args) {
;     ...
;             for (int r = 0; r < rounds; ++r) {
;                 const int p = (r & 1) ? (G - 1 - bx) : bx; const int u = r * G + p;
;                 if (u < 512) { const int qb = 15 - (u >> 5), pair = u & 31, bl = pair >> 3, j = pair & 7;
;                     attn_body::attn_unit<8>(qb, (const attn_body::bf16*)((const u16*)(wsg + WS_QC) + (size_t)(bl * 8 + j) * SEQ * 64), (const attn_body::bf16*)((const u16*)(wsg + WS_KC) + (size_t)(bl * 8 + j) * SEQ * 64),
;                                             (const attn_body::bf16*)((const u16*)(wsg + WS_VC) + (size_t)((bl * 4 + (j >> 1)) * 2) * SEQ * 64),
;                                             (attn_body::bf16*)((u16*)(wsg + WS_O) + (size_t)(bl * SEQ) * 1024 + j * 128), (char*)lds_raw); }
.LBB0_1013:
	s_bitcmp0_b32 s70, 0
	s_cselect_b32 s14, s58, s19
	s_and_b32 s0, s58, 7
	s_andn2_b32 s14, s14, 7
	s_or_b32 s14, s14, s0
	s_mul_i32 s0, s70, s60
	s_add_i32 s72, s14, s0
	s_cmpk_gt_i32 s72, 0x1ff
	s_cbranch_scc1 .LBB0_1012
	s_lshl_b32 s2, s72, 19
	s_ashr_i32 s11, s72, 5
	s_bfe_u32 s73, s72, 0x20003
	s_and_b32 s0, s2, 0xf80000
	s_add_u32 s10, s20, s0
	s_addc_u32 s13, s21, 0
	s_add_u32 s0, s22, s0
	s_addc_u32 s1, s23, 0
	s_and_b32 s2, s2, 0x300000
	s_lshl_b32 s3, s73, 22
	s_or_b32 s2, s3, s2
	v_mov_b32_e32 v36, v230
	s_add_u32 s2, s59, s2
	s_addc_u32 s3, s61, 0
	v_readfirstlane_b32 s15, v36
	s_ashr_i32 s71, s15, 6
	s_lshl_b32 s16, s11, 8
	s_lshl_b32 s17, s71, 5
	s_sub_i32 s6, s17, s16
	s_addk_i32 s6, 0xf00
	s_ashr_i32 s7, s6, 31
	v_and_b32_e32 v247, 63, v36
	s_lshl_b64 s[8:9], s[6:7], 7
	s_add_u32 s12, s10, s8
	v_lshlrev_b32_e32 v220, 7, v247
	s_addc_u32 s13, s13, s9
	v_lshl_add_u64 v[0:1], s[0:1], 0, v[220:221]
	s_lshl_b32 s0, s71, 3
	s_ashr_i32 s1, s0, 31
	s_lshl_b32 s8, s71, 4
	v_bfe_u32 v224, v36, 2, 4
	v_lshl_add_u64 v[32:33], s[0:1], 1, v[0:1]
	v_and_or_b32 v0, s8, 48, v224
	v_lshlrev_b32_e32 v0, 7, v0
	v_mov_b32_e32 v1, v221
	v_lshl_add_u64 v[0:1], s[2:3], 0, v[0:1]
	s_ashr_i32 s2, s15, 3
	s_and_b32 s8, s2, 0xffffffe0
	s_ashr_i32 s9, s8, 31
	s_lshl_b32 s10, s71, 10
	v_lshlrev_b32_e32 v249, 3, v36
	s_cmp_lg_u32 0, -1
	v_and_b32_e32 v250, 24, v249
	s_cselect_b32 s2, 0, 0
	v_lshl_add_u64 v[0:1], s[8:9], 1, v[0:1]
	v_lshlrev_b32_e32 v2, 1, v250
	v_mov_b32_e32 v3, v221
	s_add_i32 s28, s10, s2
	s_mov_b32 s2, m0
	s_mov_b32 m0, s28
	s_nop 0
	global_load_lds_dwordx4 v[32:33], off
	s_mov_b32 m0, s2
	v_lshl_add_u64 v[34:35], v[0:1], 0, v[2:3]
	s_add_i32 s33, s28, 0x6000
	s_mov_b32 s2, m0
	s_mov_b32 m0, s33
	s_nop 0
	global_load_lds_dwordx4 v[34:35], off
	s_mov_b32 m0, s2
	s_mov_b64 s[2:3], 0x80000
	v_lshl_add_u64 v[0:1], v[34:35], 0, s[2:3]
	s_add_i32 s37, s28, 0xc000
	s_mov_b32 s2, m0
	s_mov_b32 m0, s37
	s_nop 0
	global_load_lds_dwordx4 v[0:1], off
	s_mov_b32 m0, s2
	s_mov_b64 s[2:3], 0x2000
	v_and_b32_e32 v248, 31, v36
	v_lshl_add_u64 v[0:1], v[32:33], 0, s[2:3]
	v_bfe_u32 v246, v36, 5, 1
	s_add_i32 s2, s28, 0x2000
	s_mov_b32 s3, m0
	s_mov_b32 m0, s2
	s_nop 0
	global_load_lds_dwordx4 v[0:1], off
	s_mov_b32 m0, s3
	v_lshlrev_b32_e32 v0, 7, v248
	v_lshl_or_b32 v0, v246, 4, v0
	v_mov_b32_e32 v1, v221
	v_lshl_add_u64 v[14:15], s[12:13], 0, v[0:1]
	flat_load_dwordx4 v[172:175], v[14:15]
	flat_load_dwordx4 v[168:171], v[14:15] offset:32
	flat_load_dwordx4 v[156:159], v[14:15] offset:64
	flat_load_dwordx4 v[148:151], v[14:15] offset:96
	v_mov_b32_e32 v0, v221
	v_mov_b32_e32 v2, v221
	v_mov_b32_e32 v4, v221
	v_mov_b32_e32 v5, v221
	v_mov_b32_e32 v6, v221
	v_mov_b32_e32 v7, v221
	v_mov_b32_e32 v8, v221
	v_mov_b32_e32 v9, v221
	v_mov_b32_e32 v10, v221
	v_mov_b32_e32 v11, v221
	v_mov_b32_e32 v12, v221
	v_mov_b32_e32 v13, v221
	v_mov_b32_e32 v14, v221
	v_mov_b32_e32 v15, v221
	v_lshlrev_b32_e32 v16, 10, v246
	v_lshlrev_b32_e32 v17, 4, v248
	v_add3_u32 v243, 0, v16, v17
	v_lshl_add_u64 v[16:17], v[32:33], 0, s[34:35]
	s_add_i32 s2, s28, 0x4000
	s_mov_b32 s3, m0
	s_mov_b32 m0, s2
	s_nop 0
	global_load_lds_dwordx4 v[16:17], off
	s_mov_b32 m0, s3
	s_waitcnt vmcnt(4) lgkmcnt(0)
	s_barrier
	ds_read_b128 v[38:41], v243
	s_cmp_lg_u32 s11, 15
	s_cselect_b64 s[2:3], -1, 0
	v_lshlrev_b32_e32 v254, 2, v246
	v_or_b32_e32 v241, s17, v248
	s_and_b64 vcc, exec, s[2:3]
	s_waitcnt vmcnt(0) lgkmcnt(0)
	v_mfma_f32_32x32x16_bf16 v[16:31], v[38:41], v[172:175], v[0:15]
	ds_read_b128 v[38:41], v243 offset:512
	s_waitcnt lgkmcnt(0)
	v_mfma_f32_32x32x16_bf16 v[0:15], v[38:41], v[172:175], v[0:15]
	ds_read_b128 v[38:41], v243 offset:2048
	s_waitcnt lgkmcnt(0)
	v_mfma_f32_32x32x16_bf16 v[16:31], v[38:41], v[168:171], v[16:31]
	ds_read_b128 v[38:41], v243 offset:2560
	s_waitcnt lgkmcnt(0)
	v_mfma_f32_32x32x16_bf16 v[0:15], v[38:41], v[168:171], v[0:15]
	ds_read_b128 v[38:41], v243 offset:4096
	s_waitcnt lgkmcnt(0)
	v_mfma_f32_32x32x16_bf16 v[16:31], v[38:41], v[156:159], v[16:31]
	ds_read_b128 v[38:41], v243 offset:4608
	s_waitcnt lgkmcnt(0)
	v_mfma_f32_32x32x16_bf16 v[0:15], v[38:41], v[156:159], v[0:15]
	ds_read_b128 v[38:41], v243 offset:6144
	s_waitcnt lgkmcnt(0)
	v_mfma_f32_32x32x16_bf16 v[16:31], v[38:41], v[148:151], v[16:31]
	ds_read_b128 v[38:41], v243 offset:6656
	s_waitcnt lgkmcnt(0)
	v_mfma_f32_32x32x16_bf16 v[0:15], v[38:41], v[148:151], v[0:15]
	s_nop 15
	s_nop 7
	s_cbranch_vccnz .LBB0_1016
; __device__ __forceinline__ void cmask(f32x16&p0,f32x16&p1,int jb,int qrel,int hi){
;   const float NEG=-INFINITY; int kb=64*jb+4*hi;
;   #pragma unroll
;   for(int r=0;r<16;++r){int kv=kb+(r&3)+8*(r>>2); if(kv>qrel)p0[r]=NEG; if(kv+32>qrel)p1[r]=NEG;}
; }
	v_or_b32_e32 v37, 32, v254
	v_cmp_le_i32_e32 vcc, v37, v241
	v_or_b32_e32 v37, 33, v254
	s_nop 7
	v_cndmask_b32_e32 v0, v234, v0, vcc
	v_cmp_lt_i32_e32 vcc, v254, v241
	s_nop 1
	v_cndmask_b32_e32 v17, v234, v17, vcc
	v_cmp_le_i32_e32 vcc, v254, v241
	s_nop 1
	v_cndmask_b32_e32 v16, v234, v16, vcc
	v_cmp_le_i32_e32 vcc, v37, v241
	v_or_b32_e32 v37, 2, v254
	s_nop 0
	v_cndmask_b32_e32 v1, v234, v1, vcc
	v_cmp_le_i32_e32 vcc, v37, v241
	v_or_b32_e32 v37, 34, v254
	s_nop 0
	v_cndmask_b32_e32 v18, v234, v18, vcc
	v_cmp_le_i32_e32 vcc, v37, v241
	v_or_b32_e32 v37, 3, v254
	s_nop 0
	v_cndmask_b32_e32 v2, v234, v2, vcc
	v_cmp_le_i32_e32 vcc, v37, v241
	v_or_b32_e32 v37, 35, v254
	s_nop 0
	v_cndmask_b32_e32 v19, v234, v19, vcc
	v_cmp_le_i32_e32 vcc, v37, v241
	v_or_b32_e32 v37, 8, v254
	s_nop 0
	v_cndmask_b32_e32 v3, v234, v3, vcc
	v_cmp_le_i32_e32 vcc, v37, v241
	v_or_b32_e32 v37, 40, v254
	s_nop 0
	v_cndmask_b32_e32 v20, v234, v20, vcc
	v_cmp_le_i32_e32 vcc, v37, v241
	v_or_b32_e32 v37, 9, v254
	s_nop 0
	v_cndmask_b32_e32 v4, v234, v4, vcc
	v_cmp_le_i32_e32 vcc, v37, v241
	v_or_b32_e32 v37, 41, v254
	s_nop 0
	v_cndmask_b32_e32 v21, v234, v21, vcc
	v_cmp_le_i32_e32 vcc, v37, v241
	v_or_b32_e32 v37, 10, v254
	s_nop 0
	v_cndmask_b32_e32 v5, v234, v5, vcc
	v_cmp_le_i32_e32 vcc, v37, v241
	v_or_b32_e32 v37, 42, v254
	s_nop 0
	v_cndmask_b32_e32 v22, v234, v22, vcc
	v_cmp_le_i32_e32 vcc, v37, v241
	v_or_b32_e32 v37, 11, v254
	s_nop 0
	v_cndmask_b32_e32 v6, v234, v6, vcc
	v_cmp_le_i32_e32 vcc, v37, v241
	v_or_b32_e32 v37, 43, v254
	s_nop 0
	v_cndmask_b32_e32 v23, v234, v23, vcc
	v_cmp_le_i32_e32 vcc, v37, v241
	v_or_b32_e32 v37, 16, v254
	s_nop 0
	v_cndmask_b32_e32 v7, v234, v7, vcc
	v_cmp_le_i32_e32 vcc, v37, v241
	v_or_b32_e32 v37, 48, v254
	s_nop 0
	v_cndmask_b32_e32 v24, v234, v24, vcc
	v_cmp_le_i32_e32 vcc, v37, v241
	v_or_b32_e32 v37, 17, v254
	s_nop 0
	v_cndmask_b32_e32 v8, v234, v8, vcc
	v_cmp_le_i32_e32 vcc, v37, v241
	v_or_b32_e32 v37, 49, v254
	s_nop 0
	v_cndmask_b32_e32 v25, v234, v25, vcc
	v_cmp_le_i32_e32 vcc, v37, v241
	v_or_b32_e32 v37, 18, v254
	s_nop 0
	v_cndmask_b32_e32 v9, v234, v9, vcc
	v_cmp_le_i32_e32 vcc, v37, v241
	v_or_b32_e32 v37, 50, v254
	s_nop 0
	v_cndmask_b32_e32 v26, v234, v26, vcc
	v_cmp_le_i32_e32 vcc, v37, v241
	v_or_b32_e32 v37, 19, v254
	s_nop 0
	v_cndmask_b32_e32 v10, v234, v10, vcc
	v_cmp_le_i32_e32 vcc, v37, v241
	v_or_b32_e32 v37, 51, v254
	s_nop 0
	v_cndmask_b32_e32 v27, v234, v27, vcc
	v_cmp_le_i32_e32 vcc, v37, v241
	v_or_b32_e32 v37, 24, v254
	s_nop 0
	v_cndmask_b32_e32 v11, v234, v11, vcc
	v_cmp_le_i32_e32 vcc, v37, v241
	v_or_b32_e32 v37, 56, v254
	s_nop 0
	v_cndmask_b32_e32 v28, v234, v28, vcc
	v_cmp_le_i32_e32 vcc, v37, v241
	v_or_b32_e32 v37, 25, v254
	s_nop 0
	v_cndmask_b32_e32 v12, v234, v12, vcc
	v_cmp_le_i32_e32 vcc, v37, v241
	v_or_b32_e32 v37, 57, v254
	s_nop 0
	v_cndmask_b32_e32 v29, v234, v29, vcc
	v_cmp_le_i32_e32 vcc, v37, v241
	v_or_b32_e32 v37, 26, v254
	s_nop 0
	v_cndmask_b32_e32 v13, v234, v13, vcc
	v_cmp_le_i32_e32 vcc, v37, v241
	v_or_b32_e32 v37, 58, v254
	s_nop 0
	v_cndmask_b32_e32 v30, v234, v30, vcc
	v_cmp_le_i32_e32 vcc, v37, v241
	v_or_b32_e32 v37, 27, v254
	s_nop 0
	v_cndmask_b32_e32 v14, v234, v14, vcc
	v_cmp_le_i32_e32 vcc, v37, v241
	v_or_b32_e32 v37, 59, v254
	s_nop 0
	v_cndmask_b32_e32 v31, v234, v31, vcc
	v_cmp_le_i32_e32 vcc, v37, v241
	s_nop 1
	v_cndmask_b32_e32 v15, v234, v15, vcc
